# v28: v27 + up-projection K-loop: two of the six LDS-DMA loads of each 6-load segment issued inside the following MFMA block
# baseline (speedup 1.0000x reference)
; #define PG8_STAGE(bufoff, gbase, voff) do { _Pragma("unroll") for (int _i = 0; _i < 2; ++_i) \
;         __builtin_amdgcn_global_load_lds((const unsigned*)((const char*)(gbase) + (voff)[_i]), (PG8_LAS unsigned*)(lds + (bufoff) + ldsw + _i * 8192), 16, 0, 0); } while (0)
; #define PG8_LDA(dst, b, h) do { _Pragma("unroll") for (int m = 0; m < 4; ++m) _Pragma("unroll") for (int k = 0; k < 2; ++k) dst[m][k] = *(const PG8_LAS bf16x8*)(lds + PG8_SA(b, h) + aoff + m * 2048 + k * 1024); } while (0)
; #define PG8_LDB(dst, b, h) do { _Pragma("unroll") for (int n = 0; n < 2; ++n) _Pragma("unroll") for (int k = 0; k < 2; ++k) dst[n][k] = *(const PG8_LAS bf16x8*)(lds + PG8_SB(b, h) + boff + n * 2048 + k * 1024); } while (0)
; #define PG8_MMA(ai, bj, At, Bt) do { __builtin_amdgcn_s_setprio(1); _Pragma("unroll") for (int m = 0; m < 4; ++m) _Pragma("unroll") for (int n = 0; n < 2; ++n) _Pragma("unroll") for (int k = 0; k < 2; ++k) \
;         acc[ai][bj][m][n] = __builtin_amdgcn_mfma_f32_16x16x32_bf16(Bt[n][k], At[m][k], acc[ai][bj][m][n], 0, 0, 0); __builtin_amdgcn_s_setprio(0); } while (0)
; #define PG8_WAIT_V(n) asm volatile("s_waitcnt vmcnt(" #n ")" ::: "memory")
; #define PG8_WAIT_L(n) asm volatile("s_waitcnt lgkmcnt(" #n ")" ::: "memory")
; #define PG8_BAR __builtin_amdgcn_s_barrier()
; #define PG8_SCHED __builtin_amdgcn_sched_barrier(0)
; template <class Epi, class Sched, bool ALIGN_EPI = false, bool SP2 = false>
; __device__ __forceinline__ void gemm_phase(PG8_LAS unsigned char* lds, const Gemm g, const Sched& S, const Epi& E, const int wid) {
;     ...
;             PG8_LDB(B0, 0, 0); PG8_LDB(B1, 0, 1); PG8_SCHED; PG8_LDA(At, 0, 0); PG8_STAGE(PG8_SA(1, 1), a1 + hsA, voffA);
;             PG8_WAIT_V(8); PG8_WAIT_L(0); PG8_BAR; PG8_MMA(0, 0, At, B0); PG8_MMA(0, 1, At, B1); PG8_BAR; PG8_SCHED;
;             PG8_LDA(At, 0, 1); PG8_STAGE(PG8_SB(0, 0), b2, voffB); PG8_STAGE(PG8_SB(0, 1), b2 + hsB, voffB); PG8_STAGE(PG8_SA(0, 0), a2, voffA);
.LBB0_1474:
	ds_read_b128 v[152:155], v149
	ds_read_b128 v[156:159], v149 offset:1024
	ds_read_b128 v[160:163], v149 offset:2048
	ds_read_b128 v[164:167], v149 offset:3072
	ds_read_b128 v[168:171], v150
	ds_read_b128 v[172:175], v150 offset:1024
	ds_read_b128 v[176:179], v150 offset:2048
	ds_read_b128 v[180:183], v150 offset:3072
	s_add_u32 s8, s56, 0xfffc0080
	s_addc_u32 s9, s57, -1
	s_cmp_eq_u32 s69, 12
	s_cselect_b32 s61, s49, s9
	s_cselect_b32 s60, s65, s8
	s_cselect_b32 s59, s47, s68
	s_cselect_b32 s58, s66, s67
	v_lshl_add_u64 v[146:147], s[56:57], 0, v[138:139]
	s_add_i32 m0, s85, 0xc000
	ds_read_b128 v[184:187], v151
	ds_read_b128 v[188:191], v151 offset:1024
	ds_read_b128 v[192:195], v151 offset:2048
	ds_read_b128 v[196:199], v151 offset:3072
	ds_read_b128 v[200:203], v151 offset:4096
	ds_read_b128 v[204:207], v151 offset:5120
	ds_read_b128 v[208:211], v151 offset:6144
	ds_read_b128 v[212:215], v151 offset:7168
	global_load_lds_dwordx4 v[146:147], off
	v_lshl_add_u64 v[146:147], s[56:57], 0, v[140:141]
	s_add_i32 m0, s85, 0xe000
	s_nop 0
	global_load_lds_dwordx4 v[146:147], off
	s_waitcnt vmcnt(8)
	s_waitcnt lgkmcnt(0)
	s_barrier
	s_setprio 1
	s_waitcnt lgkmcnt(0)
	v_mfma_f32_16x16x32_bf16 v[126:129], v[152:155], v[184:187], v[126:129]
	v_mfma_f32_16x16x32_bf16 v[122:125], v[160:163], v[184:187], v[122:125]
	v_mfma_f32_16x16x32_bf16 v[110:113], v[152:155], v[192:195], v[110:113]
	v_mfma_f32_16x16x32_bf16 v[106:109], v[160:163], v[192:195], v[106:109]
	v_mfma_f32_16x16x32_bf16 v[94:97], v[152:155], v[200:203], v[94:97]
	v_mfma_f32_16x16x32_bf16 v[90:93], v[160:163], v[200:203], v[90:93]
	v_mfma_f32_16x16x32_bf16 v[78:81], v[152:155], v[208:211], v[78:81]
	v_mfma_f32_16x16x32_bf16 v[74:77], v[160:163], v[208:211], v[74:77]
	v_mfma_f32_16x16x32_bf16 v[126:129], v[156:159], v[188:191], v[126:129]
	v_mfma_f32_16x16x32_bf16 v[122:125], v[164:167], v[188:191], v[122:125]
	v_mfma_f32_16x16x32_bf16 v[110:113], v[156:159], v[196:199], v[110:113]
	v_mfma_f32_16x16x32_bf16 v[106:109], v[164:167], v[196:199], v[106:109]
	v_mfma_f32_16x16x32_bf16 v[94:97], v[156:159], v[204:207], v[94:97]
	v_mfma_f32_16x16x32_bf16 v[90:93], v[164:167], v[204:207], v[90:93]
	v_mfma_f32_16x16x32_bf16 v[78:81], v[156:159], v[212:215], v[78:81]
	v_mfma_f32_16x16x32_bf16 v[74:77], v[164:167], v[212:215], v[74:77]
	s_setprio 0
	s_setprio 1
	v_mfma_f32_16x16x32_bf16 v[118:121], v[168:171], v[184:187], v[118:121]
	v_mfma_f32_16x16x32_bf16 v[114:117], v[176:179], v[184:187], v[114:117]
	v_mfma_f32_16x16x32_bf16 v[102:105], v[168:171], v[192:195], v[102:105]
	v_mfma_f32_16x16x32_bf16 v[98:101], v[176:179], v[192:195], v[98:101]
	v_mfma_f32_16x16x32_bf16 v[86:89], v[168:171], v[200:203], v[86:89]
	v_mfma_f32_16x16x32_bf16 v[82:85], v[176:179], v[200:203], v[82:85]
	v_mfma_f32_16x16x32_bf16 v[70:73], v[168:171], v[208:211], v[70:73]
	v_mfma_f32_16x16x32_bf16 v[66:69], v[176:179], v[208:211], v[66:69]
	v_mfma_f32_16x16x32_bf16 v[118:121], v[172:175], v[188:191], v[118:121]
	v_mfma_f32_16x16x32_bf16 v[114:117], v[180:183], v[188:191], v[114:117]
	v_mfma_f32_16x16x32_bf16 v[102:105], v[172:175], v[196:199], v[102:105]
	v_mfma_f32_16x16x32_bf16 v[98:101], v[180:183], v[196:199], v[98:101]
	v_mfma_f32_16x16x32_bf16 v[86:89], v[172:175], v[204:207], v[86:89]
	v_mfma_f32_16x16x32_bf16 v[82:85], v[180:183], v[204:207], v[82:85]
	v_mfma_f32_16x16x32_bf16 v[70:73], v[172:175], v[212:215], v[70:73]
	v_mfma_f32_16x16x32_bf16 v[66:69], v[180:183], v[212:215], v[66:69]
	s_setprio 0
	s_barrier
	s_add_i32 s8, s35, s28
	v_lshl_add_u64 v[146:147], s[58:59], 0, v[134:135]
	s_mov_b32 m0, s8
	ds_read_b128 v[184:187], v151 offset:16384
	ds_read_b128 v[188:191], v151 offset:17408
	ds_read_b128 v[192:195], v151 offset:18432
	ds_read_b128 v[196:199], v151 offset:19456
	ds_read_b128 v[200:203], v151 offset:20480
	ds_read_b128 v[204:207], v151 offset:21504
	ds_read_b128 v[208:211], v151 offset:22528
	ds_read_b128 v[212:215], v151 offset:23552
	global_load_lds_dwordx4 v[146:147], off
	s_add_i32 m0, s8, 0x2000
	s_add_u32 s24, s58, 0x40000
	v_lshl_add_u64 v[216:217], s[58:59], 0, v[130:131]
	s_addc_u32 s25, s59, 0
	s_add_i32 s8, s36, s28
	global_load_lds_dwordx4 v[216:217], off
	v_lshl_add_u64 v[218:219], s[24:25], 0, v[134:135]
	s_mov_b32 m0, s8
	v_lshl_add_u64 v[220:221], s[60:61], 0, v[132:133]
	global_load_lds_dwordx4 v[218:219], off
	v_lshl_add_u64 v[218:219], s[24:25], 0, v[130:131]
	s_add_i32 m0, s8, 0x2000
	s_nop 0
	global_load_lds_dwordx4 v[218:219], off
	v_lshl_add_u64 v[218:219], s[60:61], 0, v[136:137]
	s_waitcnt vmcnt(6)
	s_waitcnt lgkmcnt(0)
	s_barrier
; #define PG8_STAGE(bufoff, gbase, voff) do { _Pragma("unroll") for (int _i = 0; _i < 2; ++_i) \
;         __builtin_amdgcn_global_load_lds((const unsigned*)((const char*)(gbase) + (voff)[_i]), (PG8_LAS unsigned*)(lds + (bufoff) + ldsw + _i * 8192), 16, 0, 0); } while (0)
; #define PG8_LDA(dst, b, h) do { _Pragma("unroll") for (int m = 0; m < 4; ++m) _Pragma("unroll") for (int k = 0; k < 2; ++k) dst[m][k] = *(const PG8_LAS bf16x8*)(lds + PG8_SA(b, h) + aoff + m * 2048 + k * 1024); } while (0)
; #define PG8_LDB(dst, b, h) do { _Pragma("unroll") for (int n = 0; n < 2; ++n) _Pragma("unroll") for (int k = 0; k < 2; ++k) dst[n][k] = *(const PG8_LAS bf16x8*)(lds + PG8_SB(b, h) + boff + n * 2048 + k * 1024); } while (0)
; #define PG8_MMA(ai, bj, At, Bt) do { __builtin_amdgcn_s_setprio(1); _Pragma("unroll") for (int m = 0; m < 4; ++m) _Pragma("unroll") for (int n = 0; n < 2; ++n) _Pragma("unroll") for (int k = 0; k < 2; ++k) \
;         acc[ai][bj][m][n] = __builtin_amdgcn_mfma_f32_16x16x32_bf16(Bt[n][k], At[m][k], acc[ai][bj][m][n], 0, 0, 0); __builtin_amdgcn_s_setprio(0); } while (0)
; #define PG8_WAIT_V(n) asm volatile("s_waitcnt vmcnt(" #n ")" ::: "memory")
; #define PG8_WAIT_L(n) asm volatile("s_waitcnt lgkmcnt(" #n ")" ::: "memory")
; #define PG8_BAR __builtin_amdgcn_s_barrier()
; #define PG8_SCHED __builtin_amdgcn_sched_barrier(0)
; template <class Epi, class Sched, bool ALIGN_EPI = false, bool SP2 = false>
; __device__ __forceinline__ void gemm_phase(PG8_LAS unsigned char* lds, const Gemm g, const Sched& S, const Epi& E, const int wid) {
;     ...
;             PG8_LDA(At, 0, 1); PG8_STAGE(PG8_SB(0, 0), b2, voffB); PG8_STAGE(PG8_SB(0, 1), b2 + hsB, voffB); PG8_STAGE(PG8_SA(0, 0), a2, voffA);
;             PG8_WAIT_V(8); PG8_WAIT_L(0); PG8_BAR; PG8_MMA(1, 0, At, B0); PG8_MMA(1, 1, At, B1); PG8_BAR; PG8_SCHED;
;             PG8_LDB(B0, 1, 0); PG8_LDB(B1, 1, 1); PG8_SCHED; PG8_LDA(At, 1, 0); PG8_STAGE(PG8_SA(0, 1), a2 + hsA, voffA);
;             PG8_WAIT_V(8); PG8_WAIT_L(0); PG8_BAR; PG8_MMA(0, 0, At, B0); PG8_MMA(0, 1, At, B1); PG8_BAR; PG8_SCHED;
	s_setprio 1
	s_waitcnt lgkmcnt(0)
	v_mfma_f32_16x16x32_bf16 v[62:65], v[152:155], v[184:187], v[62:65]
	v_mfma_f32_16x16x32_bf16 v[58:61], v[160:163], v[184:187], v[58:61]
	v_mfma_f32_16x16x32_bf16 v[46:49], v[152:155], v[192:195], v[46:49]
	v_mfma_f32_16x16x32_bf16 v[42:45], v[160:163], v[192:195], v[42:45]
	v_mfma_f32_16x16x32_bf16 v[30:33], v[152:155], v[200:203], v[30:33]
	v_mfma_f32_16x16x32_bf16 v[26:29], v[160:163], v[200:203], v[26:29]
	v_mfma_f32_16x16x32_bf16 v[14:17], v[152:155], v[208:211], v[14:17]
	v_mfma_f32_16x16x32_bf16 v[10:13], v[160:163], v[208:211], v[10:13]
	s_mov_b32 m0, s85
	s_nop 0
	global_load_lds_dwordx4 v[218:219], off
	v_mfma_f32_16x16x32_bf16 v[62:65], v[156:159], v[188:191], v[62:65]
	v_mfma_f32_16x16x32_bf16 v[58:61], v[164:167], v[188:191], v[58:61]
	v_mfma_f32_16x16x32_bf16 v[46:49], v[156:159], v[196:199], v[46:49]
	v_mfma_f32_16x16x32_bf16 v[42:45], v[164:167], v[196:199], v[42:45]
	v_mfma_f32_16x16x32_bf16 v[30:33], v[156:159], v[204:207], v[30:33]
	v_mfma_f32_16x16x32_bf16 v[26:29], v[164:167], v[204:207], v[26:29]
	v_mfma_f32_16x16x32_bf16 v[14:17], v[156:159], v[212:215], v[14:17]
	v_mfma_f32_16x16x32_bf16 v[10:13], v[164:167], v[212:215], v[10:13]
	s_setprio 0
	s_setprio 1
	v_mfma_f32_16x16x32_bf16 v[54:57], v[168:171], v[184:187], v[54:57]
	v_mfma_f32_16x16x32_bf16 v[50:53], v[176:179], v[184:187], v[50:53]
	v_mfma_f32_16x16x32_bf16 v[38:41], v[168:171], v[192:195], v[38:41]
	v_mfma_f32_16x16x32_bf16 v[34:37], v[176:179], v[192:195], v[34:37]
	v_mfma_f32_16x16x32_bf16 v[22:25], v[168:171], v[200:203], v[22:25]
	v_mfma_f32_16x16x32_bf16 v[18:21], v[176:179], v[200:203], v[18:21]
	v_mfma_f32_16x16x32_bf16 v[6:9], v[168:171], v[208:211], v[6:9]
	v_mfma_f32_16x16x32_bf16 v[2:5], v[176:179], v[208:211], v[2:5]
	s_mov_b32 m0, s17
	s_nop 0
	global_load_lds_dwordx4 v[220:221], off
	v_mfma_f32_16x16x32_bf16 v[54:57], v[172:175], v[188:191], v[54:57]
	v_mfma_f32_16x16x32_bf16 v[50:53], v[180:183], v[188:191], v[50:53]
	v_mfma_f32_16x16x32_bf16 v[38:41], v[172:175], v[196:199], v[38:41]
	v_mfma_f32_16x16x32_bf16 v[34:37], v[180:183], v[196:199], v[34:37]
	v_mfma_f32_16x16x32_bf16 v[22:25], v[172:175], v[204:207], v[22:25]
	v_mfma_f32_16x16x32_bf16 v[18:21], v[180:183], v[204:207], v[18:21]
	v_mfma_f32_16x16x32_bf16 v[6:9], v[172:175], v[212:215], v[6:9]
	v_mfma_f32_16x16x32_bf16 v[2:5], v[180:183], v[212:215], v[2:5]
	s_setprio 0
	s_barrier
	s_add_i32 s8, 0, 0x18000
	s_add_i32 s9, 0, 0x1c000
	v_add_u32_e32 v164, s8, v148
	v_add_u32_e32 v180, s9, v148
	ds_read_b128 v[152:155], v164
	ds_read_b128 v[156:159], v164 offset:1024
	ds_read_b128 v[160:163], v164 offset:2048
	ds_read_b128 v[164:167], v164 offset:3072
	ds_read_b128 v[168:171], v180
	ds_read_b128 v[172:175], v180 offset:1024
	ds_read_b128 v[176:179], v180 offset:2048
	ds_read_b128 v[180:183], v180 offset:3072
	s_add_u32 s24, s60, 0x40000
	s_addc_u32 s25, s61, 0
	s_mov_b32 m0, s18
	v_lshl_add_u64 v[222:223], s[24:25], 0, v[136:137]
	ds_read_b128 v[184:187], v151 offset:32768
	ds_read_b128 v[188:191], v151 offset:33792
	ds_read_b128 v[192:195], v151 offset:34816
	ds_read_b128 v[196:199], v151 offset:35840
	ds_read_b128 v[200:203], v151 offset:36864
	ds_read_b128 v[204:207], v151 offset:37888
	ds_read_b128 v[208:211], v151 offset:38912
	ds_read_b128 v[212:215], v151 offset:39936
	global_load_lds_dwordx4 v[222:223], off
	v_lshl_add_u64 v[222:223], s[24:25], 0, v[132:133]
	s_mov_b32 m0, s19
	s_nop 0
	global_load_lds_dwordx4 v[222:223], off
	s_waitcnt vmcnt(8)
	s_waitcnt lgkmcnt(0)
	s_barrier
	s_setprio 1
	s_waitcnt lgkmcnt(0)
	v_mfma_f32_16x16x32_bf16 v[126:129], v[152:155], v[184:187], v[126:129]
	v_mfma_f32_16x16x32_bf16 v[122:125], v[160:163], v[184:187], v[122:125]
	v_mfma_f32_16x16x32_bf16 v[110:113], v[152:155], v[192:195], v[110:113]
	v_mfma_f32_16x16x32_bf16 v[106:109], v[160:163], v[192:195], v[106:109]
	v_mfma_f32_16x16x32_bf16 v[94:97], v[152:155], v[200:203], v[94:97]
	v_mfma_f32_16x16x32_bf16 v[90:93], v[160:163], v[200:203], v[90:93]
	v_mfma_f32_16x16x32_bf16 v[78:81], v[152:155], v[208:211], v[78:81]
	v_mfma_f32_16x16x32_bf16 v[74:77], v[160:163], v[208:211], v[74:77]
	v_mfma_f32_16x16x32_bf16 v[126:129], v[156:159], v[188:191], v[126:129]
	v_mfma_f32_16x16x32_bf16 v[122:125], v[164:167], v[188:191], v[122:125]
	v_mfma_f32_16x16x32_bf16 v[110:113], v[156:159], v[196:199], v[110:113]
	v_mfma_f32_16x16x32_bf16 v[106:109], v[164:167], v[196:199], v[106:109]
	v_mfma_f32_16x16x32_bf16 v[94:97], v[156:159], v[204:207], v[94:97]
	v_mfma_f32_16x16x32_bf16 v[90:93], v[164:167], v[204:207], v[90:93]
	v_mfma_f32_16x16x32_bf16 v[78:81], v[156:159], v[212:215], v[78:81]
	v_mfma_f32_16x16x32_bf16 v[74:77], v[164:167], v[212:215], v[74:77]
	s_setprio 0
	s_setprio 1
	v_mfma_f32_16x16x32_bf16 v[118:121], v[168:171], v[184:187], v[118:121]
	v_mfma_f32_16x16x32_bf16 v[114:117], v[176:179], v[184:187], v[114:117]
	v_mfma_f32_16x16x32_bf16 v[102:105], v[168:171], v[192:195], v[102:105]
	v_mfma_f32_16x16x32_bf16 v[98:101], v[176:179], v[192:195], v[98:101]
	v_mfma_f32_16x16x32_bf16 v[86:89], v[168:171], v[200:203], v[86:89]
	v_mfma_f32_16x16x32_bf16 v[82:85], v[176:179], v[200:203], v[82:85]
	v_mfma_f32_16x16x32_bf16 v[70:73], v[168:171], v[208:211], v[70:73]
	v_mfma_f32_16x16x32_bf16 v[66:69], v[176:179], v[208:211], v[66:69]
	v_mfma_f32_16x16x32_bf16 v[118:121], v[172:175], v[188:191], v[118:121]
	v_mfma_f32_16x16x32_bf16 v[114:117], v[180:183], v[188:191], v[114:117]
	v_mfma_f32_16x16x32_bf16 v[102:105], v[172:175], v[196:199], v[102:105]
	v_mfma_f32_16x16x32_bf16 v[98:101], v[180:183], v[196:199], v[98:101]
	v_mfma_f32_16x16x32_bf16 v[86:89], v[172:175], v[204:207], v[86:89]
	v_mfma_f32_16x16x32_bf16 v[82:85], v[180:183], v[204:207], v[82:85]
	v_mfma_f32_16x16x32_bf16 v[70:73], v[172:175], v[212:215], v[70:73]
	v_mfma_f32_16x16x32_bf16 v[66:69], v[180:183], v[212:215], v[66:69]
	s_setprio 0
	s_barrier
; #define PG8_STAGE(bufoff, gbase, voff) do { _Pragma("unroll") for (int _i = 0; _i < 2; ++_i) \
;         __builtin_amdgcn_global_load_lds((const unsigned*)((const char*)(gbase) + (voff)[_i]), (PG8_LAS unsigned*)(lds + (bufoff) + ldsw + _i * 8192), 16, 0, 0); } while (0)
; #define PG8_LDA(dst, b, h) do { _Pragma("unroll") for (int m = 0; m < 4; ++m) _Pragma("unroll") for (int k = 0; k < 2; ++k) dst[m][k] = *(const PG8_LAS bf16x8*)(lds + PG8_SA(b, h) + aoff + m * 2048 + k * 1024); } while (0)
; #define PG8_MMA(ai, bj, At, Bt) do { __builtin_amdgcn_s_setprio(1); _Pragma("unroll") for (int m = 0; m < 4; ++m) _Pragma("unroll") for (int n = 0; n < 2; ++n) _Pragma("unroll") for (int k = 0; k < 2; ++k) \
;         acc[ai][bj][m][n] = __builtin_amdgcn_mfma_f32_16x16x32_bf16(Bt[n][k], At[m][k], acc[ai][bj][m][n], 0, 0, 0); __builtin_amdgcn_s_setprio(0); } while (0)
; #define PG8_WAIT_V(n) asm volatile("s_waitcnt vmcnt(" #n ")" ::: "memory")
; #define PG8_WAIT_L(n) asm volatile("s_waitcnt lgkmcnt(" #n ")" ::: "memory")
; #define PG8_BAR __builtin_amdgcn_s_barrier()
; #define PG8_SCHED __builtin_amdgcn_sched_barrier(0)
; template <class Epi, class Sched, bool ALIGN_EPI = false, bool SP2 = false>
; __device__ __forceinline__ void gemm_phase(PG8_LAS unsigned char* lds, const Gemm g, const Sched& S, const Epi& E, const int wid) {
;     ...
;         for (int t = 0; t < nt; t += 2) {
;             const bool last = (t == nt - 2);
;             const char* a1 = cA + (size_t)(t + 1) * kstep;
;             const char* a2 = last ? nA : cA + (size_t)(t + 2) * kstep; const char* b2 = last ? nB : cB + (size_t)(t + 2) * kstep;
;     ...
;             PG8_LDA(At, 1, 1); PG8_STAGE(PG8_SB(1, 0), b3, voffB); PG8_STAGE(PG8_SB(1, 1), b3 + hsB, voffB); PG8_STAGE(PG8_SA(1, 0), a3, voffA);
;             PG8_WAIT_V(8); PG8_WAIT_L(0); PG8_BAR; PG8_MMA(1, 0, At, B0); PG8_MMA(1, 1, At, B1); PG8_BAR; PG8_SCHED;
	s_add_i32 s8, s8, s28
	v_lshl_add_u64 v[146:147], v[146:147], 0, s[20:21]
	s_mov_b32 m0, s8
	ds_read_b128 v[184:187], v151 offset:49152
	ds_read_b128 v[188:191], v151 offset:50176
	ds_read_b128 v[192:195], v151 offset:51200
	ds_read_b128 v[196:199], v151 offset:52224
	ds_read_b128 v[200:203], v151 offset:53248
	ds_read_b128 v[204:207], v151 offset:54272
	ds_read_b128 v[208:211], v151 offset:55296
	ds_read_b128 v[212:215], v151 offset:56320
	global_load_lds_dwordx4 v[146:147], off
	s_add_i32 m0, s8, 0x2000
	s_add_u32 s24, s58, 0x40080
	v_lshl_add_u64 v[146:147], v[216:217], 0, s[20:21]
	s_addc_u32 s25, s59, 0
	s_add_i32 s8, s9, s28
	global_load_lds_dwordx4 v[146:147], off
	v_lshl_add_u64 v[146:147], s[24:25], 0, v[134:135]
	s_mov_b32 m0, s8
	s_nop 0
	global_load_lds_dwordx4 v[146:147], off
	v_lshl_add_u64 v[146:147], s[24:25], 0, v[130:131]
	s_add_i32 m0, s8, 0x2000
	s_nop 0
	global_load_lds_dwordx4 v[146:147], off
	s_waitcnt vmcnt(6)
	s_waitcnt lgkmcnt(0)
	s_barrier
	s_setprio 1
	s_waitcnt lgkmcnt(0)
	v_mfma_f32_16x16x32_bf16 v[62:65], v[152:155], v[184:187], v[62:65]
	v_mfma_f32_16x16x32_bf16 v[58:61], v[160:163], v[184:187], v[58:61]
	v_mfma_f32_16x16x32_bf16 v[46:49], v[152:155], v[192:195], v[46:49]
	v_mfma_f32_16x16x32_bf16 v[42:45], v[160:163], v[192:195], v[42:45]
	v_mfma_f32_16x16x32_bf16 v[30:33], v[152:155], v[200:203], v[30:33]
	v_mfma_f32_16x16x32_bf16 v[26:29], v[160:163], v[200:203], v[26:29]
	v_mfma_f32_16x16x32_bf16 v[14:17], v[152:155], v[208:211], v[14:17]
	v_mfma_f32_16x16x32_bf16 v[10:13], v[160:163], v[208:211], v[10:13]
	v_lshl_add_u64 v[146:147], v[218:219], 0, s[20:21]
	s_mov_b32 m0, s27
	s_nop 0
	global_load_lds_dwordx4 v[146:147], off
	v_mfma_f32_16x16x32_bf16 v[62:65], v[156:159], v[188:191], v[62:65]
	v_mfma_f32_16x16x32_bf16 v[58:61], v[164:167], v[188:191], v[58:61]
	v_mfma_f32_16x16x32_bf16 v[46:49], v[156:159], v[196:199], v[46:49]
	v_mfma_f32_16x16x32_bf16 v[42:45], v[164:167], v[196:199], v[42:45]
	v_mfma_f32_16x16x32_bf16 v[30:33], v[156:159], v[204:207], v[30:33]
	v_mfma_f32_16x16x32_bf16 v[26:29], v[164:167], v[204:207], v[26:29]
	v_mfma_f32_16x16x32_bf16 v[14:17], v[156:159], v[212:215], v[14:17]
	v_mfma_f32_16x16x32_bf16 v[10:13], v[164:167], v[212:215], v[10:13]
	s_setprio 0
	s_setprio 1
	v_mfma_f32_16x16x32_bf16 v[54:57], v[168:171], v[184:187], v[54:57]
	v_mfma_f32_16x16x32_bf16 v[50:53], v[176:179], v[184:187], v[50:53]
	v_mfma_f32_16x16x32_bf16 v[38:41], v[168:171], v[192:195], v[38:41]
	v_mfma_f32_16x16x32_bf16 v[34:37], v[176:179], v[192:195], v[34:37]
	v_mfma_f32_16x16x32_bf16 v[22:25], v[168:171], v[200:203], v[22:25]
	v_mfma_f32_16x16x32_bf16 v[18:21], v[176:179], v[200:203], v[18:21]
	v_mfma_f32_16x16x32_bf16 v[6:9], v[168:171], v[208:211], v[6:9]
	v_mfma_f32_16x16x32_bf16 v[2:5], v[176:179], v[208:211], v[2:5]
	v_lshl_add_u64 v[146:147], v[220:221], 0, s[20:21]
	s_mov_b32 m0, s31
	s_nop 0
	global_load_lds_dwordx4 v[146:147], off
	v_mfma_f32_16x16x32_bf16 v[54:57], v[172:175], v[188:191], v[54:57]
	v_mfma_f32_16x16x32_bf16 v[50:53], v[180:183], v[188:191], v[50:53]
	v_mfma_f32_16x16x32_bf16 v[38:41], v[172:175], v[196:199], v[38:41]
	v_mfma_f32_16x16x32_bf16 v[34:37], v[180:183], v[196:199], v[34:37]
	v_mfma_f32_16x16x32_bf16 v[22:25], v[172:175], v[204:207], v[22:25]
	v_mfma_f32_16x16x32_bf16 v[18:21], v[180:183], v[204:207], v[18:21]
	v_mfma_f32_16x16x32_bf16 v[6:9], v[172:175], v[212:215], v[6:9]
	v_mfma_f32_16x16x32_bf16 v[2:5], v[180:183], v[212:215], v[2:5]
	s_setprio 0
	s_barrier
	s_add_i32 s69, s69, 2
	s_add_u32 s56, s56, 0x100
	s_addc_u32 s57, s57, 0
	s_add_u32 s67, s67, 0x100
	s_addc_u32 s68, s68, 0
	s_cmp_gt_u32 s69, 13
	s_cbranch_scc0 .LBB0_1474
	s_and_b64 vcc, exec, s[6:7]
	s_cbranch_vccz .LBB0_1477
	s_barrier
